# up-GEMM (P4/P11) epilogue stores made write-through (sc1) so the phase-end L2 write-back has less to flush
# baseline (speedup 1.0000x reference)
.LBB0_443:
	v_readlane_b32 s0, v255, 33
	s_add_u32 s16, s68, s0
	s_addc_u32 s17, s69, 0
	s_lshl_b32 s46, s90, 8
	s_ashr_i32 s47, s46, 31
	s_lshl_b64 s[74:75], s[46:47], 1
	s_add_u32 s0, s44, s74
	s_addc_u32 s1, s45, s75
	s_cmp_gt_i32 s90, 7
	s_mov_b64 s[26:27], s[76:77]
	s_cselect_b64 s[76:77], -1, 0
	s_add_i32 s6, s46, 0xfffff800
	s_ashr_i32 s7, s6, 31
	s_lshl_b64 s[6:7], s[6:7], 1
	s_add_u32 s6, s16, s6
	s_addc_u32 s7, s17, s7
	s_lshl_b32 s48, s90, 7
	s_ashr_i32 s49, s48, 31
	s_lshl_b64 s[48:49], s[48:49], 1
	s_add_u32 s78, s44, s48
	s_addc_u32 s79, s45, s49
	s_cmp_gt_u32 s90, 11
	s_mov_b32 s47, s53
	s_cselect_b64 s[56:57], -1, 0
	s_lshl_b64 s[48:49], s[46:47], 1
	s_add_u32 s47, s68, s48
	s_addc_u32 s48, s69, s49
	s_add_u32 s50, s47, 0x9380000
	s_addc_u32 s51, s48, 0
	s_and_b32 s63, s46, 0x300
	s_lshl_b32 s46, s63, 1
	s_cmp_lt_u32 s90, 4
	s_cselect_b32 s48, s44, s16
	s_mov_b32 s49, 0x18960000
	s_mov_b32 s52, 0x8460000
	s_cselect_b32 s47, s45, s17
	s_cselect_b32 s49, s49, 0x18d60000
	s_cselect_b32 s52, s52, 0x10460000
	s_add_u32 s80, s48, s46
	s_addc_u32 s81, s47, 0
	s_add_u32 s46, s12, s49
	s_addc_u32 s47, s13, 0
	s_add_u32 s48, s12, s52
	s_addc_u32 s49, s13, 0
	v_ashrrev_i32_e32 v169, 31, v168
	v_cmp_gt_i32_e64 s[4:5], 2, v166
	s_mov_b64 s[58:59], -1
	s_mov_b64 s[70:71], 0
	s_cmp_lt_i32 s93, 2
	s_mov_b64 s[82:83], 0
	s_cbranch_scc1 .LBB0_447
	s_cmp_eq_u32 s93, 2
	s_mov_b64 s[82:83], -1
	s_cbranch_scc0 .LBB0_446
	v_pk_mul_f32 v[134:135], v[172:173], v[130:131] op_sel_hi:[0,1]
	v_pk_mul_f32 v[132:133], v[172:173], v[128:129] op_sel_hi:[0,1]
	v_pk_mul_f32 v[136:137], v[172:173], v[126:127] op_sel_hi:[0,1]
	v_pk_mul_f32 v[138:139], v[172:173], v[124:125] op_sel_hi:[0,1]
	v_cvt_pk_bf16_f32 v132, v132, v133
	v_cvt_pk_bf16_f32 v133, v134, v135
	v_cvt_pk_bf16_f32 v134, v138, v139
	v_cvt_pk_bf16_f32 v135, v136, v137
	v_mov_b64_e32 v[136:137], s[0:1]
	s_movk_i32 s52, 0x2c00
	v_mad_i64_i32 v[136:137], s[58:59], v174, s52, v[136:137]
	v_lshl_add_u64 v[136:137], v[168:169], 1, v[136:137]
	global_store_dwordx4 v[136:137], v[132:135], off sc1
	v_pk_mul_f32 v[138:139], v[172:173], v[118:119] op_sel_hi:[0,1]
	v_pk_mul_f32 v[140:141], v[172:173], v[116:117] op_sel_hi:[0,1]
	v_pk_mul_f32 v[134:135], v[172:173], v[122:123] op_sel_hi:[0,1]
	v_pk_mul_f32 v[132:133], v[172:173], v[120:121] op_sel_hi:[0,1]
	v_cvt_pk_bf16_f32 v132, v132, v133
	v_cvt_pk_bf16_f32 v133, v134, v135
	v_cvt_pk_bf16_f32 v134, v140, v141
	v_cvt_pk_bf16_f32 v135, v138, v139
	global_store_dwordx4 v[136:137], v[132:135], off offset:256 sc1
	s_mov_b64 s[82:83], 0

.LBB0_502:
	s_cmp_eq_u32 s93, 2
	s_mov_b64 s[70:71], -1
	s_cbranch_scc0 .LBB0_504
	v_pk_mul_f32 v[134:135], v[172:173], v[114:115] op_sel:[1,0]
	v_pk_mul_f32 v[132:133], v[172:173], v[112:113] op_sel:[1,0]
	v_pk_mul_f32 v[136:137], v[172:173], v[110:111] op_sel:[1,0]
	v_pk_mul_f32 v[138:139], v[172:173], v[108:109] op_sel:[1,0]
	v_cvt_pk_bf16_f32 v132, v132, v133
	v_cvt_pk_bf16_f32 v133, v134, v135
	s_movk_i32 s52, 0x2c00
	v_cvt_pk_bf16_f32 v134, v138, v139
	v_cvt_pk_bf16_f32 v135, v136, v137
	v_mov_b64_e32 v[136:137], s[0:1]
	v_mad_i64_i32 v[136:137], s[70:71], v174, s52, v[136:137]
	v_lshl_add_u64 v[136:137], v[168:169], 1, v[136:137]
	global_store_dwordx4 v[136:137], v[132:135], off sc1
	v_pk_mul_f32 v[138:139], v[172:173], v[102:103] op_sel:[1,0]
	v_pk_mul_f32 v[140:141], v[172:173], v[100:101] op_sel:[1,0]
	v_pk_mul_f32 v[134:135], v[172:173], v[106:107] op_sel:[1,0]
	v_pk_mul_f32 v[132:133], v[172:173], v[104:105] op_sel:[1,0]
	s_mov_b64 s[70:71], 0
	v_cvt_pk_bf16_f32 v132, v132, v133
	v_cvt_pk_bf16_f32 v133, v134, v135
	v_cvt_pk_bf16_f32 v134, v140, v141
	v_cvt_pk_bf16_f32 v135, v138, v139
	global_store_dwordx4 v[136:137], v[132:135], off offset:256 sc1

.LBB0_557:
	s_cmp_eq_u32 s93, 2
	s_mov_b64 s[70:71], -1
	s_cbranch_scc0 .LBB0_559
	v_pk_mul_f32 v[134:135], v[170:171], v[94:95] op_sel_hi:[0,1]
	v_pk_mul_f32 v[132:133], v[170:171], v[92:93] op_sel_hi:[0,1]
	v_pk_mul_f32 v[136:137], v[170:171], v[90:91] op_sel_hi:[0,1]
	v_pk_mul_f32 v[138:139], v[170:171], v[88:89] op_sel_hi:[0,1]
	v_cvt_pk_bf16_f32 v132, v132, v133
	v_cvt_pk_bf16_f32 v133, v134, v135
	v_cvt_pk_bf16_f32 v134, v138, v139
	v_cvt_pk_bf16_f32 v135, v136, v137
	v_mov_b64_e32 v[136:137], s[0:1]
	s_movk_i32 s52, 0x2c00
	v_mad_i64_i32 v[136:137], s[70:71], v172, s52, v[136:137]
	v_lshl_add_u64 v[136:137], v[168:169], 1, v[136:137]
	global_store_dwordx4 v[136:137], v[132:135], off sc1
	v_pk_mul_f32 v[138:139], v[170:171], v[82:83] op_sel_hi:[0,1]
	v_pk_mul_f32 v[140:141], v[170:171], v[80:81] op_sel_hi:[0,1]
	v_pk_mul_f32 v[134:135], v[170:171], v[86:87] op_sel_hi:[0,1]
	v_pk_mul_f32 v[132:133], v[170:171], v[84:85] op_sel_hi:[0,1]
	v_cvt_pk_bf16_f32 v132, v132, v133
	v_cvt_pk_bf16_f32 v133, v134, v135
	v_cvt_pk_bf16_f32 v134, v140, v141
	v_cvt_pk_bf16_f32 v135, v138, v139
	global_store_dwordx4 v[136:137], v[132:135], off offset:256 sc1
	s_mov_b64 s[70:71], 0

.LBB0_612:
	s_cmp_eq_u32 s93, 2
	s_mov_b64 s[70:71], -1
	s_cbranch_scc0 .LBB0_618
	v_pk_mul_f32 v[134:135], v[170:171], v[78:79] op_sel:[1,0]
	v_pk_mul_f32 v[132:133], v[170:171], v[76:77] op_sel:[1,0]
	v_pk_mul_f32 v[136:137], v[170:171], v[74:75] op_sel:[1,0]
	v_pk_mul_f32 v[138:139], v[170:171], v[72:73] op_sel:[1,0]
	v_cvt_pk_bf16_f32 v132, v132, v133
	v_cvt_pk_bf16_f32 v133, v134, v135
	s_movk_i32 s16, 0x2c00
	v_cvt_pk_bf16_f32 v134, v138, v139
	v_cvt_pk_bf16_f32 v135, v136, v137
	v_mov_b64_e32 v[136:137], s[0:1]
	v_add_u32_e32 v98, -14, v182
	v_mad_i64_i32 v[136:137], s[16:17], v174, s16, v[136:137]
	v_lshl_add_u64 v[136:137], v[168:169], 1, v[136:137]
	v_add_u32_e32 v98, s80, v98
	global_store_dwordx4 v[136:137], v[132:135], off sc1
	s_and_saveexec_b64 s[70:71], s[76:77]
	s_cbranch_execz .LBB0_615
	s_movk_i32 s16, 0x2c00
	v_mad_i64_i32 v[138:139], s[16:17], v98, s16, v[172:173]
	global_store_dwordx4 v[138:139], v[132:135], off sc1
.LBB0_615:
	s_or_b64 exec, exec, s[70:71]
	s_nop 0
	v_mov_b32_e32 v132, v171
	v_mov_b32_e32 v133, v171
	v_mov_b32_e32 v134, v171
	v_mov_b32_e32 v135, v171
	v_pk_mul_f32 v[138:139], v[134:135], v[70:71]
	v_pk_mul_f32 v[176:177], v[134:135], v[66:67]
	v_pk_mul_f32 v[134:135], v[132:133], v[64:65]
	v_pk_mul_f32 v[140:141], v[132:133], v[68:69]
	s_nop 0
	v_cvt_pk_bf16_f32 v132, v140, v141
	v_cvt_pk_bf16_f32 v133, v138, v139
	v_cvt_pk_bf16_f32 v134, v134, v135
	v_cvt_pk_bf16_f32 v135, v176, v177
	global_store_dwordx4 v[136:137], v[132:135], off offset:256 sc1
	s_and_saveexec_b64 s[70:71], s[76:77]
	s_cbranch_execz .LBB0_617
	v_mov_b64_e32 v[136:137], s[74:75]
	s_movk_i32 s16, 0x2c00
	v_mad_i64_i32 v[136:137], s[16:17], v98, s16, v[136:137]
	v_lshl_add_u64 v[136:137], v[168:169], 1, v[136:137]
	global_store_dwordx4 v[136:137], v[132:135], off offset:256 sc1

.LBB0_671:
	s_cmp_eq_u32 s93, 2
	s_mov_b64 s[70:71], -1
	s_cbranch_scc0 .LBB0_673
	v_pk_mul_f32 v[134:135], v[154:155], v[62:63] op_sel_hi:[0,1]
	v_pk_mul_f32 v[132:133], v[154:155], v[60:61] op_sel_hi:[0,1]
	v_pk_mul_f32 v[136:137], v[154:155], v[58:59] op_sel_hi:[0,1]
	v_pk_mul_f32 v[138:139], v[154:155], v[56:57] op_sel_hi:[0,1]
	v_cvt_pk_bf16_f32 v132, v132, v133
	v_cvt_pk_bf16_f32 v133, v134, v135
	v_cvt_pk_bf16_f32 v134, v138, v139
	v_cvt_pk_bf16_f32 v135, v136, v137
	v_mov_b64_e32 v[136:137], s[0:1]
	s_movk_i32 s16, 0x2c00
	v_mad_i64_i32 v[136:137], s[16:17], v170, s16, v[136:137]
	v_lshl_add_u64 v[136:137], v[168:169], 1, v[136:137]
	global_store_dwordx4 v[136:137], v[132:135], off sc1
	v_pk_mul_f32 v[138:139], v[154:155], v[50:51] op_sel_hi:[0,1]
	v_pk_mul_f32 v[140:141], v[154:155], v[48:49] op_sel_hi:[0,1]
	v_pk_mul_f32 v[134:135], v[154:155], v[54:55] op_sel_hi:[0,1]
	v_pk_mul_f32 v[132:133], v[154:155], v[52:53] op_sel_hi:[0,1]
	v_cvt_pk_bf16_f32 v132, v132, v133
	v_cvt_pk_bf16_f32 v133, v134, v135
	v_cvt_pk_bf16_f32 v134, v140, v141
	v_cvt_pk_bf16_f32 v135, v138, v139
	global_store_dwordx4 v[136:137], v[132:135], off offset:256 sc1
	s_mov_b64 s[70:71], 0

.LBB0_726:
	s_cmp_eq_u32 s93, 2
	s_mov_b64 s[70:71], -1
	s_cbranch_scc0 .LBB0_728
	v_pk_mul_f32 v[134:135], v[154:155], v[46:47] op_sel:[1,0]
	v_pk_mul_f32 v[132:133], v[154:155], v[44:45] op_sel:[1,0]
	v_pk_mul_f32 v[136:137], v[154:155], v[42:43] op_sel:[1,0]
	v_pk_mul_f32 v[138:139], v[154:155], v[40:41] op_sel:[1,0]
	v_cvt_pk_bf16_f32 v132, v132, v133
	v_cvt_pk_bf16_f32 v133, v134, v135
	s_movk_i32 s16, 0x2c00
	v_cvt_pk_bf16_f32 v134, v138, v139
	v_cvt_pk_bf16_f32 v135, v136, v137
	v_mov_b64_e32 v[136:137], s[0:1]
	v_mad_i64_i32 v[136:137], s[16:17], v170, s16, v[136:137]
	v_lshl_add_u64 v[136:137], v[168:169], 1, v[136:137]
	global_store_dwordx4 v[136:137], v[132:135], off sc1
	v_pk_mul_f32 v[138:139], v[154:155], v[34:35] op_sel:[1,0]
	v_pk_mul_f32 v[140:141], v[154:155], v[32:33] op_sel:[1,0]
	v_pk_mul_f32 v[134:135], v[154:155], v[38:39] op_sel:[1,0]
	v_pk_mul_f32 v[132:133], v[154:155], v[36:37] op_sel:[1,0]
	s_mov_b64 s[70:71], 0
	v_cvt_pk_bf16_f32 v132, v132, v133
	v_cvt_pk_bf16_f32 v133, v134, v135
	v_cvt_pk_bf16_f32 v134, v140, v141
	v_cvt_pk_bf16_f32 v135, v138, v139
	global_store_dwordx4 v[136:137], v[132:135], off offset:256 sc1

.LBB0_781:
	s_cmp_eq_u32 s93, 2
	s_mov_b64 s[70:71], -1
	s_cbranch_scc0 .LBB0_783
	v_pk_mul_f32 v[134:135], v[142:143], v[30:31] op_sel_hi:[0,1]
	v_pk_mul_f32 v[132:133], v[142:143], v[28:29] op_sel_hi:[0,1]
	v_pk_mul_f32 v[136:137], v[142:143], v[26:27] op_sel_hi:[0,1]
	v_pk_mul_f32 v[138:139], v[142:143], v[24:25] op_sel_hi:[0,1]
	v_cvt_pk_bf16_f32 v132, v132, v133
	v_cvt_pk_bf16_f32 v133, v134, v135
	v_cvt_pk_bf16_f32 v134, v138, v139
	v_cvt_pk_bf16_f32 v135, v136, v137
	v_mov_b64_e32 v[136:137], s[0:1]
	s_movk_i32 s16, 0x2c00
	v_mad_i64_i32 v[136:137], s[16:17], v154, s16, v[136:137]
	v_lshl_add_u64 v[136:137], v[168:169], 1, v[136:137]
	global_store_dwordx4 v[136:137], v[132:135], off sc1
	v_pk_mul_f32 v[138:139], v[142:143], v[18:19] op_sel_hi:[0,1]
	v_pk_mul_f32 v[140:141], v[142:143], v[16:17] op_sel_hi:[0,1]
	v_pk_mul_f32 v[134:135], v[142:143], v[22:23] op_sel_hi:[0,1]
	v_pk_mul_f32 v[132:133], v[142:143], v[20:21] op_sel_hi:[0,1]
	v_cvt_pk_bf16_f32 v132, v132, v133
	v_cvt_pk_bf16_f32 v133, v134, v135
	v_cvt_pk_bf16_f32 v134, v140, v141
	v_cvt_pk_bf16_f32 v135, v138, v139
	global_store_dwordx4 v[136:137], v[132:135], off offset:256 sc1
	s_mov_b64 s[70:71], 0

.LBB0_832:
	v_add_u32_e32 v154, v180, v189
	s_mov_b64 s[78:79], -1
	s_mov_b64 s[68:69], 0
	s_cmp_lt_i32 s93, 2
	s_mov_b64 s[70:71], 0
	s_cbranch_scc1 .LBB0_840
	s_cmp_eq_u32 s93, 2
	s_mov_b64 s[70:71], -1
	s_cbranch_scc0 .LBB0_839
	v_pk_mul_f32 v[134:135], v[142:143], v[14:15] op_sel:[1,0]
	v_pk_mul_f32 v[132:133], v[142:143], v[12:13] op_sel:[1,0]
	v_pk_mul_f32 v[136:137], v[142:143], v[10:11] op_sel:[1,0]
	v_pk_mul_f32 v[138:139], v[142:143], v[8:9] op_sel:[1,0]
	v_cvt_pk_bf16_f32 v132, v132, v133
	v_cvt_pk_bf16_f32 v133, v134, v135
	v_add_u32_e32 v98, -12, v182
	v_cvt_pk_bf16_f32 v134, v138, v139
	v_cvt_pk_bf16_f32 v135, v136, v137
	v_mov_b64_e32 v[136:137], s[0:1]
	s_movk_i32 s0, 0x2c00
	v_mad_i64_i32 v[136:137], s[0:1], v154, s0, v[136:137]
	v_lshl_add_u64 v[136:137], v[168:169], 1, v[136:137]
	v_add_u32_e32 v98, s80, v98
	global_store_dwordx4 v[136:137], v[132:135], off sc1
	s_and_saveexec_b64 s[0:1], s[76:77]
	s_cbranch_execz .LBB0_836
	s_movk_i32 s16, 0x2c00
	v_mad_i64_i32 v[138:139], s[16:17], v98, s16, v[172:173]
	global_store_dwordx4 v[138:139], v[132:135], off sc1
.LBB0_836:
	s_or_b64 exec, exec, s[0:1]
	s_nop 0
	v_mov_b32_e32 v132, v143
	v_mov_b32_e32 v133, v143
	v_mov_b32_e32 v134, v143
	v_mov_b32_e32 v135, v143
	v_pk_mul_f32 v[138:139], v[134:135], v[6:7]
	v_pk_mul_f32 v[170:171], v[134:135], v[2:3]
	v_pk_mul_f32 v[134:135], v[132:133], v[0:1]
	v_pk_mul_f32 v[140:141], v[132:133], v[4:5]
	s_nop 0
	v_cvt_pk_bf16_f32 v132, v140, v141
	v_cvt_pk_bf16_f32 v133, v138, v139
	v_cvt_pk_bf16_f32 v134, v134, v135
	v_cvt_pk_bf16_f32 v135, v170, v171
	global_store_dwordx4 v[136:137], v[132:135], off offset:256 sc1
	s_and_saveexec_b64 s[0:1], s[76:77]
	s_cbranch_execz .LBB0_838
	v_mov_b64_e32 v[136:137], s[74:75]
	s_movk_i32 s16, 0x2c00
	v_mad_i64_i32 v[136:137], s[16:17], v98, s16, v[136:137]
	v_lshl_add_u64 v[136:137], v[168:169], 1, v[136:137]
	global_store_dwordx4 v[136:137], v[132:135], off offset:256 sc1
